# pair8r with the P6 wait on the four per-row gain/bias pieces moved down to their consumers as a counted vmcnt(14)
# speedup vs baseline: 1.0028x; 1.0028x over previous
; __device__ __forceinline__ void p6_final_ln(const Frame& F) {
;     ...
;     for (int m = gw; m < M; m += NGW) {
;         const float* xr = (m < SEQ) ? F.xp + (size_t)m * DM : F.xs + (size_t)(m - SEQ) * DM;
;         const bf16_t* orow = F.OUTB + (size_t)m * DM;
;         f32x4 z[16]; float s = 0.f;
; #pragma unroll
;         for (int j = 0; j < 8; ++j) { const int col = j * 512 + lane * 8;
;             const f32x4 xa = *(const f32x4*)(xr + col), xb = *(const f32x4*)(xr + col + 4); const u32x4 o = *(const u32x4*)(orow + col);
;             z[2 * j]     = xa * DN_ALPHA + (f32x4){bflo(o.x), bfhi(o.x), bflo(o.y), bfhi(o.y)};
;             z[2 * j + 1] = xb * DN_ALPHA + (f32x4){bflo(o.z), bfhi(o.z), bflo(o.w), bfhi(o.w)};
;             s += (z[2 * j][0] + z[2 * j][1]) + (z[2 * j][2] + z[2 * j][3]) + (z[2 * j + 1][0] + z[2 * j + 1][1]) + (z[2 * j + 1][2] + z[2 * j + 1][3]); }
.LBB0_575:
	s_lshl_b64 s[18:19], s[12:13], 13
	s_add_u32 s18, s26, s18
	s_addc_u32 s19, s27, s19
	v_lshlrev_b32_e32 v70, 1, v4
	global_load_dwordx4 v[42:45], v70, s[18:19]
	global_load_dwordx4 v[46:49], v70, s[18:19] offset:1024
	global_load_dwordx4 v[50:53], v70, s[18:19] offset:2048
	v_lshlrev_b32_e32 v109, 2, v4
	global_load_dwordx4 v[54:57], v109, s[16:17]
	global_load_dwordx4 v[58:61], v109, s[16:17] offset:16
	global_load_dwordx4 v[62:65], v109, s[16:17] offset:2048
	global_load_dwordx4 v[66:69], v109, s[16:17] offset:2064
	global_load_dwordx4 v[74:77], v104, s[16:17]
	global_load_dwordx4 v[78:81], v104, s[16:17] offset:16
	global_load_dwordx4 v[0:3], v105, s[16:17] offset:16
	global_load_dwordx4 v[82:85], v105, s[16:17]
	v_lshlrev_b32_e32 v107, 2, v6
	v_lshlrev_b32_e32 v71, 1, v6
	v_lshlrev_b32_e32 v108, 2, v8
	v_lshlrev_b32_e32 v72, 1, v8
	global_load_dwordx4 v[86:89], v107, s[16:17] offset:16
	global_load_dwordx4 v[94:97], v107, s[16:17]
	global_load_dwordx4 v[112:115], v108, s[16:17] offset:16
	global_load_dwordx4 v[116:119], v108, s[16:17]
	global_load_dwordx4 v[98:101], v70, s[18:19] offset:3072
	global_load_dwordx4 v[120:123], v71, s[18:19]
	global_load_dwordx4 v[124:127], v72, s[18:19]
	s_lshl_b64 s[12:13], s[12:13], 14
	s_add_u32 s12, s38, s12
	s_addc_u32 s13, s39, s13
	s_add_u32 s0, s0, s2
	s_addc_u32 s1, s1, s3
	s_add_u32 s6, s6, s8
	s_addc_u32 s7, s7, s9
	s_cmpk_lt_i32 s0, 0x6000
	s_barrier
	s_waitcnt vmcnt(17)
	v_lshlrev_b32_e32 v70, 16, v42
	v_and_b32_e32 v71, 0xffff0000, v42
	v_lshlrev_b32_e32 v42, 16, v43
	v_and_b32_e32 v43, 0xffff0000, v43
	v_lshlrev_b32_e32 v72, 16, v44
	v_and_b32_e32 v73, 0xffff0000, v44
	v_lshlrev_b32_e32 v44, 16, v45
	v_and_b32_e32 v45, 0xffff0000, v45
	s_waitcnt vmcnt(16)
	v_lshlrev_b32_e32 v110, 16, v46
	v_and_b32_e32 v111, 0xffff0000, v46
	v_lshlrev_b32_e32 v46, 16, v47
	v_and_b32_e32 v47, 0xffff0000, v47
	v_lshlrev_b32_e32 v128, 16, v48
	v_and_b32_e32 v129, 0xffff0000, v48
	v_lshlrev_b32_e32 v48, 16, v49
	v_and_b32_e32 v49, 0xffff0000, v49
	s_waitcnt vmcnt(14)
	v_pk_fma_f32 v[90:91], v[56:57], s[10:11], v[42:43] op_sel_hi:[1,0,1]
	v_pk_fma_f32 v[92:93], v[54:55], s[10:11], v[70:71] op_sel_hi:[1,0,1]
	s_waitcnt vmcnt(13)
	v_pk_fma_f32 v[70:71], v[60:61], s[10:11], v[44:45] op_sel_hi:[1,0,1]
	v_pk_fma_f32 v[72:73], v[58:59], s[10:11], v[72:73] op_sel_hi:[1,0,1]
	s_waitcnt vmcnt(12)
	v_pk_fma_f32 v[60:61], v[64:65], s[10:11], v[46:47] op_sel_hi:[1,0,1]
	v_pk_fma_f32 v[58:59], v[62:63], s[10:11], v[110:111] op_sel_hi:[1,0,1]
	s_waitcnt vmcnt(11)
	v_pk_fma_f32 v[56:57], v[68:69], s[10:11], v[48:49] op_sel_hi:[1,0,1]
	v_pk_fma_f32 v[54:55], v[66:67], s[10:11], v[128:129] op_sel_hi:[1,0,1]
	v_mov_b32_e32 v46, v92
	v_mov_b32_e32 v47, v58
	v_mov_b32_e32 v48, v93
	v_mov_b32_e32 v49, v59
	v_mov_b32_e32 v62, v90
	v_mov_b32_e32 v63, v60
	v_mov_b32_e32 v64, v91
	v_mov_b32_e32 v65, v61
	v_lshlrev_b32_e32 v130, 16, v50
	v_and_b32_e32 v131, 0xffff0000, v50
	v_lshlrev_b32_e32 v50, 16, v51
	v_and_b32_e32 v51, 0xffff0000, v51
	v_mov_b32_e32 v66, v72
	v_mov_b32_e32 v67, v54
	v_mov_b32_e32 v68, v73
	v_mov_b32_e32 v69, v55
	v_pk_add_f32 v[46:47], v[46:47], v[48:49]
	v_pk_add_f32 v[48:49], v[62:63], v[64:65]
	v_lshlrev_b32_e32 v132, 16, v52
	v_and_b32_e32 v133, 0xffff0000, v52
	v_lshlrev_b32_e32 v134, 16, v53
	v_and_b32_e32 v135, 0xffff0000, v53
	s_waitcnt vmcnt(10)
	v_pk_fma_f32 v[52:53], v[76:77], s[10:11], v[50:51] op_sel_hi:[1,0,1]
	v_pk_fma_f32 v[50:51], v[74:75], s[10:11], v[130:131] op_sel_hi:[1,0,1]
	v_mov_b32_e32 v74, v70
	v_mov_b32_e32 v75, v56
	v_mov_b32_e32 v76, v71
	v_mov_b32_e32 v77, v57
	v_pk_add_f32 v[62:63], v[66:67], v[68:69]
	v_pk_add_f32 v[46:47], v[46:47], v[48:49]
	v_pk_add_f32 v[64:65], v[74:75], v[76:77]
	v_pk_add_f32 v[46:47], v[62:63], v[46:47]
	s_waitcnt vmcnt(9)
	v_pk_fma_f32 v[44:45], v[80:81], s[10:11], v[134:135] op_sel_hi:[1,0,1]
	v_pk_fma_f32 v[42:43], v[78:79], s[10:11], v[132:133] op_sel_hi:[1,0,1]
	v_pk_mov_b32 v[78:79], v[50:51], v[52:53] op_sel:[1,0]
	v_mov_b32_e32 v80, v50
	v_mov_b32_e32 v81, v53
	v_pk_add_f32 v[46:47], v[64:65], v[46:47]
	v_pk_add_f32 v[66:67], v[78:79], v[80:81]
	v_add_f32_e32 v46, 0, v46
	v_mov_b32_e32 v48, v44
	v_mov_b32_e32 v49, v42
	v_mov_b32_e32 v62, v45
	v_mov_b32_e32 v63, v43
	v_add_f32_e32 v76, v46, v47
	v_pk_add_f32 v[46:47], v[66:67], v[66:67] op_sel:[0,1] op_sel_hi:[1,0]
	v_pk_add_f32 v[62:63], v[48:49], v[62:63]
	v_lshlrev_b32_e32 v111, 2, v10
	v_pk_add_f32 v[64:65], v[62:63], v[46:47] op_sel:[1,0] op_sel_hi:[0,1]
	v_lshlrev_b32_e32 v46, 1, v10
	global_load_dwordx4 v[46:49], v46, s[18:19]
	v_pk_add_f32 v[78:79], v[62:63], v[64:65]
	global_load_dwordx4 v[62:65], v111, s[16:17] offset:16
	global_load_dwordx4 v[66:69], v111, s[16:17]
	v_lshlrev_b32_e32 v77, 1, v12
	global_load_dwordx4 v[128:131], v77, s[18:19]
	v_lshlrev_b32_e32 v110, 2, v12
	global_load_dwordx4 v[132:135], v110, s[16:17] offset:16
	global_load_dwordx4 v[136:139], v110, s[16:17]
	s_waitcnt vmcnt(8)
	v_lshlrev_b32_e32 v74, 16, v98
	v_and_b32_e32 v75, 0xffff0000, v98
	v_lshlrev_b32_e32 v80, 16, v99
	v_and_b32_e32 v81, 0xffff0000, v99
	v_pk_fma_f32 v[80:81], v[84:85], s[10:11], v[80:81] op_sel_hi:[1,0,1]
	v_pk_fma_f32 v[74:75], v[82:83], s[10:11], v[74:75] op_sel_hi:[1,0,1]
	v_lshlrev_b32_e32 v82, 16, v100
	v_and_b32_e32 v83, 0xffff0000, v100
	v_lshlrev_b32_e32 v84, 16, v101
	v_and_b32_e32 v85, 0xffff0000, v101
	v_pk_fma_f32 v[100:101], v[2:3], s[10:11], v[84:85] op_sel_hi:[1,0,1]
	v_pk_fma_f32 v[98:99], v[0:1], s[10:11], v[82:83] op_sel_hi:[1,0,1]
	s_waitcnt vmcnt(7)
; __device__ __forceinline__ float wave_sum(float v) {
; #pragma unroll
;     for (int o = 1; o < 64; o <<= 1) v += __shfl_xor(v, o);
;     return v;
; __device__ __forceinline__ void p6_final_ln(const Frame& F) {
;     ...
;         for (int j = 0; j < 8; ++j) { const int col = j * 512 + lane * 8;
;             const f32x4 xa = *(const f32x4*)(xr + col), xb = *(const f32x4*)(xr + col + 4); const u32x4 o = *(const u32x4*)(orow + col);
;             z[2 * j]     = xa * DN_ALPHA + (f32x4){bflo(o.x), bfhi(o.x), bflo(o.y), bfhi(o.y)};
;             z[2 * j + 1] = xb * DN_ALPHA + (f32x4){bflo(o.z), bfhi(o.z), bflo(o.w), bfhi(o.w)};
;             s += (z[2 * j][0] + z[2 * j][1]) + (z[2 * j][2] + z[2 * j][3]) + (z[2 * j + 1][0] + z[2 * j + 1][1]) + (z[2 * j + 1][2] + z[2 * j + 1][3]); }
;         const float mean = wave_sum(s) * (1.f / DM); float q = 0.f;
	v_lshlrev_b32_e32 v82, 16, v120
	v_and_b32_e32 v83, 0xffff0000, v120
	v_lshlrev_b32_e32 v84, 16, v121
	v_and_b32_e32 v85, 0xffff0000, v121
	v_pk_fma_f32 v[96:97], v[96:97], s[10:11], v[84:85] op_sel_hi:[1,0,1]
	v_pk_fma_f32 v[94:95], v[94:95], s[10:11], v[82:83] op_sel_hi:[1,0,1]
	v_lshlrev_b32_e32 v82, 16, v122
	v_and_b32_e32 v83, 0xffff0000, v122
	v_lshlrev_b32_e32 v84, 16, v123
	v_and_b32_e32 v85, 0xffff0000, v123
	v_add_f32_e32 v0, v74, v75
	v_add_f32_e32 v2, v80, v81
	v_pk_fma_f32 v[84:85], v[88:89], s[10:11], v[84:85] op_sel_hi:[1,0,1]
	v_pk_fma_f32 v[82:83], v[86:87], s[10:11], v[82:83] op_sel_hi:[1,0,1]
	v_mov_b32_e32 v86, v98
	v_mov_b32_e32 v87, v94
	v_mov_b32_e32 v88, v99
	v_mov_b32_e32 v89, v95
	v_mov_b32_e32 v1, v96
	v_mov_b32_e32 v3, v97
	v_pk_add_f32 v[86:87], v[86:87], v[88:89]
	v_pk_add_f32 v[0:1], v[0:1], v[2:3]
	v_mov_b32_e32 v2, v100
	v_pk_add_f32 v[0:1], v[86:87], v[0:1]
	v_mov_b32_e32 v3, v82
	v_mov_b32_e32 v86, v101
	v_mov_b32_e32 v87, v83
	v_pk_add_f32 v[2:3], v[2:3], v[86:87]
	v_mov_b32_e32 v77, v84
	v_mov_b32_e32 v79, v85
	v_pk_add_f32 v[0:1], v[2:3], v[0:1]
	v_pk_add_f32 v[2:3], v[76:77], v[78:79]
	s_nop 0
	v_pk_add_f32 v[0:1], v[2:3], v[0:1]
	s_waitcnt vmcnt(6)
	v_lshlrev_b32_e32 v2, 16, v125
	v_pk_add_f32 v[120:121], v[0:1], v[0:1] op_sel:[0,1] op_sel_hi:[1,0]
	v_lshlrev_b32_e32 v0, 16, v124
	v_and_b32_e32 v1, 0xffff0000, v124
	v_and_b32_e32 v3, 0xffff0000, v125
	v_pk_fma_f32 v[88:89], v[118:119], s[10:11], v[2:3] op_sel_hi:[1,0,1]
	v_pk_fma_f32 v[86:87], v[116:117], s[10:11], v[0:1] op_sel_hi:[1,0,1]
	v_lshlrev_b32_e32 v0, 16, v126
	v_and_b32_e32 v1, 0xffff0000, v126
	v_lshlrev_b32_e32 v2, 16, v127
	v_and_b32_e32 v3, 0xffff0000, v127
	v_pk_fma_f32 v[78:79], v[114:115], s[10:11], v[2:3] op_sel_hi:[1,0,1]
	v_pk_fma_f32 v[76:77], v[112:113], s[10:11], v[0:1] op_sel_hi:[1,0,1]
	v_pk_mov_b32 v[0:1], v[86:87], v[88:89] op_sel:[1,0]
	v_mov_b32_e32 v2, v86
	v_mov_b32_e32 v3, v89
	v_pk_add_f32 v[0:1], v[0:1], v[2:3]
	v_mov_b32_e32 v2, v78
	v_mov_b32_e32 v3, v76
	v_mov_b32_e32 v112, v79
	v_mov_b32_e32 v113, v77
	v_pk_add_f32 v[0:1], v[0:1], v[0:1] op_sel:[0,1] op_sel_hi:[1,0]
	v_pk_add_f32 v[2:3], v[2:3], v[112:113]
	s_nop 0
	v_pk_add_f32 v[0:1], v[2:3], v[0:1] op_sel:[1,0] op_sel_hi:[0,1]
	v_pk_add_f32 v[112:113], v[2:3], v[0:1]
	s_waitcnt vmcnt(5)
	v_lshlrev_b32_e32 v0, 16, v46
	v_and_b32_e32 v1, 0xffff0000, v46
	v_lshlrev_b32_e32 v2, 16, v47
	v_and_b32_e32 v3, 0xffff0000, v47
	s_waitcnt vmcnt(3)
	v_pk_fma_f32 v[68:69], v[68:69], s[10:11], v[2:3] op_sel_hi:[1,0,1]
	v_pk_fma_f32 v[66:67], v[66:67], s[10:11], v[0:1] op_sel_hi:[1,0,1]
	v_lshlrev_b32_e32 v0, 16, v48
	v_and_b32_e32 v1, 0xffff0000, v48
	v_lshlrev_b32_e32 v2, 16, v49
	v_and_b32_e32 v3, 0xffff0000, v49
	v_pk_fma_f32 v[64:65], v[64:65], s[10:11], v[2:3] op_sel_hi:[1,0,1]
	v_pk_fma_f32 v[62:63], v[62:63], s[10:11], v[0:1] op_sel_hi:[1,0,1]
	s_waitcnt vmcnt(2)
	v_lshlrev_b32_e32 v2, 16, v128
	v_and_b32_e32 v3, 0xffff0000, v128
	v_lshlrev_b32_e32 v0, 16, v129
	v_and_b32_e32 v1, 0xffff0000, v129
	s_waitcnt vmcnt(0)
	v_pk_fma_f32 v[0:1], v[138:139], s[10:11], v[0:1] op_sel_hi:[1,0,1]
	v_pk_fma_f32 v[2:3], v[136:137], s[10:11], v[2:3] op_sel_hi:[1,0,1]
	v_add_f32_e32 v114, v66, v67
	v_add_f32_e32 v116, v68, v69
	v_lshlrev_b32_e32 v48, 16, v130
	v_and_b32_e32 v49, 0xffff0000, v130
	v_mov_b32_e32 v118, v62
	v_mov_b32_e32 v119, v2
	v_mov_b32_e32 v122, v63
	v_mov_b32_e32 v123, v3
	v_mov_b32_e32 v115, v0
	v_mov_b32_e32 v117, v1
	v_lshlrev_b32_e32 v46, 16, v131
	v_and_b32_e32 v47, 0xffff0000, v131
	v_pk_fma_f32 v[48:49], v[132:133], s[10:11], v[48:49] op_sel_hi:[1,0,1]
	v_pk_add_f32 v[118:119], v[118:119], v[122:123]
	v_pk_add_f32 v[114:115], v[114:115], v[116:117]
	v_pk_fma_f32 v[46:47], v[134:135], s[10:11], v[46:47] op_sel_hi:[1,0,1]
	v_pk_add_f32 v[114:115], v[118:119], v[114:115]
	v_mov_b32_e32 v116, v64
	v_mov_b32_e32 v117, v48
	v_mov_b32_e32 v118, v65
	v_mov_b32_e32 v119, v49
	v_pk_add_f32 v[116:117], v[116:117], v[118:119]
	v_mov_b32_e32 v121, v46
	v_mov_b32_e32 v113, v47
	v_pk_add_f32 v[114:115], v[116:117], v[114:115]
	v_pk_add_f32 v[112:113], v[120:121], v[112:113]
	s_nop 0
	v_pk_add_f32 v[112:113], v[112:113], v[114:115]
	s_nop 0
	v_add_f32_e32 v102, v112, v113
	ds_bpermute_b32 v112, v5, v102
	s_waitcnt lgkmcnt(0)
	v_add_f32_e32 v102, v102, v112
	ds_bpermute_b32 v112, v7, v102
	s_waitcnt lgkmcnt(0)
	v_add_f32_e32 v102, v102, v112
	ds_bpermute_b32 v112, v9, v102
	s_waitcnt lgkmcnt(0)
	v_add_f32_e32 v102, v102, v112
	ds_bpermute_b32 v112, v11, v102
	s_waitcnt lgkmcnt(0)
	v_add_f32_e32 v102, v102, v112
	ds_bpermute_b32 v112, v13, v102
	s_waitcnt lgkmcnt(0)
	v_add_f32_e32 v102, v102, v112
	ds_bpermute_b32 v112, v103, v102
	s_waitcnt lgkmcnt(0)
; __device__ __forceinline__ void p6_final_ln(const Frame& F) {
;     ...
;         const float mean = wave_sum(s) * (1.f / DM); float q = 0.f;
; #pragma unroll
;         for (int j = 0; j < 16; ++j) { const f32x4 d = z[j] - mean; z[j] = d; q += (d[0] * d[0] + d[1] * d[1]) + (d[2] * d[2] + d[3] * d[3]); }
;         const float rstd = __builtin_amdgcn_rsqf(wave_sum(q) * (1.f / DM) + LN_EPS);
;         float* yr = F.out + (size_t)m * DM;
; #pragma unroll
;         for (int j = 0; j < 8; ++j) { const int col = j * 512 + lane * 8;
;             const f32x4 ga = *(const f32x4*)(F.ln_g + col), gb = *(const f32x4*)(F.ln_g + col + 4), ba = *(const f32x4*)(F.ln_b + col), bb = *(const f32x4*)(F.ln_b + col + 4);
	v_add_f32_e32 v136, v102, v112
	v_fmamk_f32 v93, v136, 0xb9800000, v93
	v_fmac_f32_e32 v92, 0xb9800000, v136
	v_fmamk_f32 v91, v136, 0xb9800000, v91
	v_fmac_f32_e32 v90, 0xb9800000, v136
	v_pk_mul_f32 v[112:113], v[90:91], v[90:91]
	v_pk_mul_f32 v[114:115], v[92:93], v[92:93]
	v_fmamk_f32 v73, v136, 0xb9800000, v73
	v_pk_mov_b32 v[116:117], v[114:115], v[112:113] op_sel:[1,0]
	v_mov_b32_e32 v115, v113
	v_fmac_f32_e32 v72, 0xb9800000, v136
	v_fmamk_f32 v71, v136, 0xb9800000, v71
	v_fmac_f32_e32 v70, 0xb9800000, v136
	v_pk_add_f32 v[112:113], v[116:117], v[114:115]
	v_pk_mul_f32 v[114:115], v[70:71], v[70:71]
	v_pk_mul_f32 v[116:117], v[72:73], v[72:73]
	v_fmac_f32_e32 v58, 0xb9800000, v136
	v_pk_mov_b32 v[118:119], v[116:117], v[114:115] op_sel:[1,0]
	v_mov_b32_e32 v117, v115
	v_fmamk_f32 v59, v136, 0xb9800000, v59
	v_fmac_f32_e32 v60, 0xb9800000, v136
	v_mul_f32_e32 v102, v58, v58
	v_pk_add_f32 v[114:115], v[118:119], v[116:117]
	v_fmamk_f32 v61, v136, 0xb9800000, v61
	v_pk_fma_f32 v[116:117], v[58:59], v[58:59], v[102:103] op_sel_hi:[1,1,0]
	v_mul_f32_e32 v102, v60, v60
	v_pk_add_f32 v[112:113], v[112:113], v[112:113] op_sel_hi:[0,1]
	v_pk_add_f32 v[114:115], v[114:115], v[114:115] op_sel_hi:[0,1]
	v_pk_fma_f32 v[118:119], v[60:61], v[60:61], v[102:103] op_sel_hi:[1,1,0]
	v_fmamk_f32 v57, v136, 0xb9800000, v57
	v_fmac_f32_e32 v56, 0xb9800000, v136
	v_fmamk_f32 v55, v136, 0xb9800000, v55
	v_fmac_f32_e32 v54, 0xb9800000, v136
	v_mul_f32_e32 v116, v54, v54
	v_mul_f32_e32 v118, v55, v55
	v_mul_f32_e32 v112, v56, v56
	v_mul_f32_e32 v114, v57, v57
	v_pk_add_f32 v[116:117], v[116:117], v[118:119]
	v_pk_add_f32 v[112:113], v[112:113], v[114:115]
	v_fmamk_f32 v51, v136, 0xb9800000, v51
	v_fmac_f32_e32 v50, 0xb9800000, v136
	v_fmamk_f32 v53, v136, 0xb9800000, v53
	v_fmac_f32_e32 v52, 0xb9800000, v136
	v_pk_add_f32 v[112:113], v[116:117], v[112:113]
	v_pk_mul_f32 v[114:115], v[52:53], v[52:53]
	v_pk_mul_f32 v[116:117], v[50:51], v[50:51]
	v_fmac_f32_e32 v42, 0xb9800000, v136
	v_pk_mov_b32 v[118:119], v[116:117], v[114:115] op_sel:[1,0]
	v_mov_b32_e32 v117, v115
	v_fmamk_f32 v43, v136, 0xb9800000, v43
	v_fmac_f32_e32 v44, 0xb9800000, v136
	v_mul_f32_e32 v102, v42, v42
	v_pk_add_f32 v[114:115], v[118:119], v[116:117]
	v_fmamk_f32 v45, v136, 0xb9800000, v45
	v_pk_fma_f32 v[116:117], v[42:43], v[42:43], v[102:103] op_sel_hi:[1,1,0]
	v_mul_f32_e32 v102, v44, v44
	v_pk_add_f32 v[112:113], v[112:113], v[112:113] op_sel_hi:[0,1]
	v_pk_add_f32 v[114:115], v[114:115], v[114:115] op_sel_hi:[0,1]
	v_pk_fma_f32 v[118:119], v[44:45], v[44:45], v[102:103] op_sel_hi:[1,1,0]
	v_fmamk_f32 v81, v136, 0xb9800000, v81
	v_fmac_f32_e32 v80, 0xb9800000, v136
	v_fmamk_f32 v75, v136, 0xb9800000, v75
	v_fmac_f32_e32 v74, 0xb9800000, v136
	v_mul_f32_e32 v116, v74, v74
	v_mul_f32_e32 v118, v75, v75
	v_mul_f32_e32 v114, v80, v80
	v_mul_f32_e32 v112, v81, v81
	v_pk_add_f32 v[116:117], v[116:117], v[118:119]
	v_pk_add_f32 v[112:113], v[114:115], v[112:113]
	v_fmamk_f32 v99, v136, 0xb9800000, v99
	v_fmac_f32_e32 v98, 0xb9800000, v136
	v_fmamk_f32 v101, v136, 0xb9800000, v101
	v_fmac_f32_e32 v100, 0xb9800000, v136
	v_pk_add_f32 v[112:113], v[116:117], v[112:113]
	v_pk_mul_f32 v[114:115], v[100:101], v[100:101]
	v_pk_mul_f32 v[116:117], v[98:99], v[98:99]
	v_fmac_f32_e32 v94, 0xb9800000, v136
	v_pk_mov_b32 v[118:119], v[116:117], v[114:115] op_sel:[1,0]
	v_mov_b32_e32 v117, v115
	v_fmamk_f32 v95, v136, 0xb9800000, v95
	v_fmac_f32_e32 v96, 0xb9800000, v136
	v_mul_f32_e32 v102, v94, v94
	v_pk_add_f32 v[114:115], v[118:119], v[116:117]
	v_fmamk_f32 v97, v136, 0xb9800000, v97
	v_pk_fma_f32 v[116:117], v[94:95], v[94:95], v[102:103] op_sel_hi:[1,1,0]
	v_mul_f32_e32 v102, v96, v96
	v_pk_add_f32 v[112:113], v[112:113], v[112:113] op_sel_hi:[0,1]
	v_pk_add_f32 v[114:115], v[114:115], v[114:115] op_sel_hi:[0,1]
	v_pk_fma_f32 v[118:119], v[96:97], v[96:97], v[102:103] op_sel_hi:[1,1,0]
	v_fmamk_f32 v85, v136, 0xb9800000, v85
	v_fmac_f32_e32 v84, 0xb9800000, v136
	v_fmamk_f32 v83, v136, 0xb9800000, v83
	v_fmac_f32_e32 v82, 0xb9800000, v136
	v_mul_f32_e32 v116, v82, v82
	v_mul_f32_e32 v118, v83, v83
	v_mul_f32_e32 v114, v84, v84
	v_mul_f32_e32 v112, v85, v85
	v_pk_add_f32 v[116:117], v[116:117], v[118:119]
	v_pk_add_f32 v[112:113], v[114:115], v[112:113]
	v_fmamk_f32 v87, v136, 0xb9800000, v87
	v_pk_add_f32 v[112:113], v[116:117], v[112:113]
	v_fmac_f32_e32 v86, 0xb9800000, v136
	v_fmamk_f32 v89, v136, 0xb9800000, v89
	v_fmac_f32_e32 v88, 0xb9800000, v136
	v_pk_add_f32 v[128:129], v[112:113], v[112:113] op_sel_hi:[0,1]
	v_pk_mul_f32 v[112:113], v[88:89], v[88:89]
	v_pk_mul_f32 v[114:115], v[86:87], v[86:87]
	v_fmac_f32_e32 v76, 0xb9800000, v136
	v_pk_mov_b32 v[116:117], v[114:115], v[112:113] op_sel:[1,0]
	v_mov_b32_e32 v115, v113
	v_pk_add_f32 v[112:113], v[116:117], v[114:115]
	v_fmamk_f32 v77, v136, 0xb9800000, v77
	v_pk_add_f32 v[130:131], v[112:113], v[112:113] op_sel_hi:[0,1]
	global_load_dwordx4 v[112:115], v[40:41], off
	global_load_dwordx4 v[116:119], v[38:39], off
	global_load_dwordx4 v[120:123], v[38:39], off offset:16
	global_load_dwordx4 v[124:127], v[40:41], off offset:16
	v_fmac_f32_e32 v78, 0xb9800000, v136
	v_mul_f32_e32 v102, v76, v76
	v_fmamk_f32 v79, v136, 0xb9800000, v79
	v_pk_fma_f32 v[132:133], v[76:77], v[76:77], v[102:103] op_sel_hi:[1,1,0]
	v_mul_f32_e32 v102, v78, v78
	v_pk_fma_f32 v[134:135], v[78:79], v[78:79], v[102:103] op_sel_hi:[1,1,0]
	v_fmamk_f32 v69, v136, 0xb9800000, v69
	v_fmac_f32_e32 v68, 0xb9800000, v136
	v_fmamk_f32 v67, v136, 0xb9800000, v67
	v_fmac_f32_e32 v66, 0xb9800000, v136
	v_mul_f32_e32 v132, v66, v66
	v_mul_f32_e32 v134, v67, v67
; __device__ __forceinline__ void p6_final_ln(const Frame& F) {
;     ...
;         for (int j = 0; j < 16; ++j) { const f32x4 d = z[j] - mean; z[j] = d; q += (d[0] * d[0] + d[1] * d[1]) + (d[2] * d[2] + d[3] * d[3]); }
;         const float rstd = __builtin_amdgcn_rsqf(wave_sum(q) * (1.f / DM) + LN_EPS);
	v_mul_f32_e32 v130, v68, v68
	v_mul_f32_e32 v128, v69, v69
	v_pk_add_f32 v[132:133], v[132:133], v[134:135]
	v_pk_add_f32 v[128:129], v[130:131], v[128:129]
	v_fmamk_f32 v63, v136, 0xb9800000, v63
	v_fmac_f32_e32 v62, 0xb9800000, v136
	v_fmamk_f32 v65, v136, 0xb9800000, v65
	v_fmac_f32_e32 v64, 0xb9800000, v136
	v_pk_add_f32 v[128:129], v[132:133], v[128:129]
	v_pk_mul_f32 v[130:131], v[64:65], v[64:65]
	v_pk_mul_f32 v[132:133], v[62:63], v[62:63]
	v_fmac_f32_e32 v2, 0xb9800000, v136
	v_pk_mov_b32 v[134:135], v[132:133], v[130:131] op_sel:[1,0]
	v_mov_b32_e32 v133, v131
	v_fmamk_f32 v3, v136, 0xb9800000, v3
	v_fmac_f32_e32 v0, 0xb9800000, v136
	v_mul_f32_e32 v102, v2, v2
	v_pk_add_f32 v[130:131], v[134:135], v[132:133]
	v_fmamk_f32 v1, v136, 0xb9800000, v1
	v_pk_fma_f32 v[132:133], v[2:3], v[2:3], v[102:103] op_sel_hi:[1,1,0]
	v_mul_f32_e32 v102, v0, v0
	v_pk_add_f32 v[128:129], v[128:129], v[128:129] op_sel_hi:[0,1]
	v_pk_add_f32 v[130:131], v[130:131], v[130:131] op_sel_hi:[0,1]
	v_pk_fma_f32 v[134:135], v[0:1], v[0:1], v[102:103] op_sel_hi:[1,1,0]
	v_fmamk_f32 v47, v136, 0xb9800000, v47
	v_fmac_f32_e32 v46, 0xb9800000, v136
	v_fmamk_f32 v49, v136, 0xb9800000, v49
	v_fmac_f32_e32 v48, 0xb9800000, v136
	v_mul_f32_e32 v132, v48, v48
	v_mul_f32_e32 v134, v49, v49
	v_mul_f32_e32 v130, v46, v46
	v_mul_f32_e32 v128, v47, v47
	v_pk_add_f32 v[132:133], v[132:133], v[134:135]
	v_pk_add_f32 v[128:129], v[130:131], v[128:129]
	s_nop 0
	v_pk_add_f32 v[128:129], v[132:133], v[128:129]
	s_nop 0
	v_add_f32_e32 v102, v128, v129
	ds_bpermute_b32 v128, v5, v102
	s_waitcnt lgkmcnt(0)
	v_add_f32_e32 v102, v102, v128
	ds_bpermute_b32 v128, v7, v102
	s_waitcnt lgkmcnt(0)
	v_add_f32_e32 v102, v102, v128
	ds_bpermute_b32 v128, v9, v102
	s_waitcnt lgkmcnt(0)
	v_add_f32_e32 v102, v102, v128
	ds_bpermute_b32 v128, v11, v102
	s_waitcnt lgkmcnt(0)
	v_add_f32_e32 v102, v102, v128
	ds_bpermute_b32 v128, v13, v102
	s_waitcnt lgkmcnt(0)
	v_add_f32_e32 v102, v102, v128
	ds_bpermute_b32 v128, v103, v102
	s_waitcnt lgkmcnt(0)
; __device__ __forceinline__ void p6_final_ln(const Frame& F) {
;     ...
;         const float rstd = __builtin_amdgcn_rsqf(wave_sum(q) * (1.f / DM) + LN_EPS);
;         float* yr = F.out + (size_t)m * DM;
; #pragma unroll
;         for (int j = 0; j < 8; ++j) { const int col = j * 512 + lane * 8;
;             const f32x4 ga = *(const f32x4*)(F.ln_g + col), gb = *(const f32x4*)(F.ln_g + col + 4), ba = *(const f32x4*)(F.ln_b + col), bb = *(const f32x4*)(F.ln_b + col + 4);
;             *(f32x4*)(yr + col) = z[2 * j] * rstd * ga + ba; *(f32x4*)(yr + col + 4) = z[2 * j + 1] * rstd * gb + bb; }
	v_add_f32_e32 v102, v102, v128
	v_fmamk_f32 v102, v102, 0x39800000, v106
	v_rsq_f32_e32 v102, v102
	s_nop 0
	v_pk_mul_f32 v[128:129], v[92:93], v[102:103] op_sel_hi:[1,0]
	v_pk_mul_f32 v[90:91], v[90:91], v[102:103] op_sel_hi:[1,0]
	v_pk_mul_f32 v[70:71], v[70:71], v[102:103] op_sel_hi:[1,0]
	s_nop 0
	v_pk_fma_f32 v[92:93], v[146:147], v[90:91], v[154:155]
	v_pk_fma_f32 v[90:91], v[144:145], v[128:129], v[152:153]
	global_store_dwordx4 v109, v[90:93], s[12:13]
	v_pk_mul_f32 v[60:61], v[60:61], v[102:103] op_sel_hi:[1,0]
	v_pk_mul_f32 v[58:59], v[58:59], v[102:103] op_sel_hi:[1,0]
	v_pk_mul_f32 v[90:91], v[72:73], v[102:103] op_sel_hi:[1,0]
	v_pk_fma_f32 v[72:73], v[142:143], v[70:71], v[150:151]
	v_pk_fma_f32 v[70:71], v[140:141], v[90:91], v[148:149]
	global_store_dwordx4 v109, v[70:73], s[12:13] offset:16
	s_nop 0
	s_nop 0
	s_nop 0
	s_nop 0
	s_nop 0
	v_pk_mul_f32 v[56:57], v[56:57], v[102:103] op_sel_hi:[1,0]
	v_pk_mul_f32 v[54:55], v[54:55], v[102:103] op_sel_hi:[1,0]
	v_pk_mul_f32 v[52:53], v[52:53], v[102:103] op_sel_hi:[1,0]
	v_pk_mul_f32 v[50:51], v[50:51], v[102:103] op_sel_hi:[1,0]
	v_pk_mul_f32 v[44:45], v[44:45], v[102:103] op_sel_hi:[1,0]
	v_pk_mul_f32 v[42:43], v[42:43], v[102:103] op_sel_hi:[1,0]
	v_pk_mul_f32 v[76:77], v[76:77], v[102:103] op_sel_hi:[1,0]
	v_pk_mul_f32 v[68:69], v[68:69], v[102:103] op_sel_hi:[1,0]
	v_pk_mul_f32 v[66:67], v[66:67], v[102:103] op_sel_hi:[1,0]
	v_pk_mul_f32 v[64:65], v[64:65], v[102:103] op_sel_hi:[1,0]
	v_pk_mul_f32 v[62:63], v[62:63], v[102:103] op_sel_hi:[1,0]
	v_pk_mul_f32 v[46:47], v[46:47], v[102:103] op_sel_hi:[1,0]
	v_pk_mul_f32 v[48:49], v[48:49], v[102:103] op_sel_hi:[1,0]
	s_nop 0
	v_pk_fma_f32 v[58:59], v[160:161], v[58:59], v[156:157]
	v_pk_fma_f32 v[60:61], v[162:163], v[60:61], v[158:159]
	s_nop 0
	v_pk_fma_f32 v[54:55], v[164:165], v[54:55], v[168:169]
	v_pk_fma_f32 v[56:57], v[166:167], v[56:57], v[170:171]
	global_store_dwordx4 v109, v[58:61], s[12:13] offset:2048
	global_store_dwordx4 v109, v[54:57], s[12:13] offset:2064
	s_nop 0
	s_nop 0
	s_nop 0
	s_nop 0
	s_nop 0
	s_nop 0
	v_pk_fma_f32 v[50:51], v[176:177], v[50:51], v[172:173]
	v_pk_fma_f32 v[52:53], v[178:179], v[52:53], v[174:175]
	s_nop 0
	v_pk_fma_f32 v[42:43], v[180:181], v[42:43], v[184:185]
	v_pk_fma_f32 v[44:45], v[182:183], v[44:45], v[186:187]
	global_store_dwordx4 v104, v[50:53], s[12:13]
	global_store_dwordx4 v104, v[42:45], s[12:13] offset:16
	s_nop 0
	s_nop 0
	s_nop 0
	s_nop 0
	s_nop 0
	v_pk_mul_f32 v[70:71], v[80:81], v[102:103] op_sel_hi:[1,0]
	v_pk_mul_f32 v[72:73], v[74:75], v[102:103] op_sel_hi:[1,0]
	v_pk_mul_f32 v[74:75], v[84:85], v[102:103] op_sel_hi:[1,0]
	v_pk_mul_f32 v[80:81], v[82:83], v[102:103] op_sel_hi:[1,0]
	s_nop 0
	v_pk_fma_f32 v[42:43], v[192:193], v[72:73], v[188:189]
	v_pk_fma_f32 v[44:45], v[194:195], v[70:71], v[190:191]
	global_store_dwordx4 v105, v[42:45], s[12:13]
	v_pk_mul_f32 v[70:71], v[96:97], v[102:103] op_sel_hi:[1,0]
	v_pk_mul_f32 v[72:73], v[94:95], v[102:103] op_sel_hi:[1,0]
	v_pk_mul_f32 v[44:45], v[100:101], v[102:103] op_sel_hi:[1,0]
	v_pk_mul_f32 v[42:43], v[98:99], v[102:103] op_sel_hi:[1,0]
	s_nop 0
	v_pk_fma_f32 v[44:45], v[198:199], v[44:45], v[202:203]
	v_pk_fma_f32 v[42:43], v[196:197], v[42:43], v[200:201]
	global_store_dwordx4 v105, v[42:45], s[12:13] offset:16
	s_nop 0
	s_nop 0
	s_nop 0
	s_nop 0
	s_nop 0
	s_nop 0
	v_pk_fma_f32 v[42:43], v[208:209], v[72:73], v[204:205]
	v_pk_fma_f32 v[44:45], v[210:211], v[70:71], v[206:207]
	s_nop 0
	v_pk_fma_f32 v[50:51], v[212:213], v[80:81], v[216:217]
	v_pk_fma_f32 v[52:53], v[214:215], v[74:75], v[218:219]
	global_store_dwordx4 v107, v[42:45], s[12:13]
	global_store_dwordx4 v107, v[50:53], s[12:13] offset:16
	s_nop 0
	s_nop 0
	s_nop 0
	s_nop 0
	s_nop 0
	v_pk_mul_f32 v[70:71], v[88:89], v[102:103] op_sel_hi:[1,0]
	v_pk_mul_f32 v[72:73], v[86:87], v[102:103] op_sel_hi:[1,0]
	v_pk_mul_f32 v[74:75], v[78:79], v[102:103] op_sel_hi:[1,0]
	s_nop 0
	v_pk_fma_f32 v[42:43], v[224:225], v[72:73], v[220:221]
	v_pk_fma_f32 v[44:45], v[226:227], v[70:71], v[222:223]
	s_nop 0
	v_pk_fma_f32 v[50:51], v[228:229], v[76:77], v[232:233]
	v_pk_fma_f32 v[52:53], v[230:231], v[74:75], v[234:235]
	global_store_dwordx4 v108, v[42:45], s[12:13]
	global_store_dwordx4 v108, v[50:53], s[12:13] offset:16
	s_nop 0
	s_nop 0
	s_nop 0
	s_nop 0
	s_nop 0
	s_nop 0
	v_pk_fma_f32 v[42:43], v[240:241], v[66:67], v[236:237]
	v_pk_fma_f32 v[44:45], v[242:243], v[68:69], v[238:239]
	s_nop 0
	v_pk_fma_f32 v[50:51], v[244:245], v[62:63], v[248:249]
	v_pk_fma_f32 v[52:53], v[246:247], v[64:65], v[250:251]
	global_store_dwordx4 v111, v[42:45], s[12:13]
	global_store_dwordx4 v111, v[50:53], s[12:13] offset:16
	s_nop 0
	s_nop 0
	s_nop 0
	s_nop 0
	s_nop 0
	v_pk_mul_f32 v[62:63], v[0:1], v[102:103] op_sel_hi:[1,0]
	v_pk_mul_f32 v[0:1], v[2:3], v[102:103] op_sel_hi:[1,0]
	s_waitcnt vmcnt(14)
	v_pk_fma_f32 v[2:3], v[118:119], v[62:63], v[114:115]
	v_pk_fma_f32 v[0:1], v[116:117], v[0:1], v[112:113]
	s_nop 0
	v_pk_fma_f32 v[42:43], v[48:49], v[120:121], v[124:125]
	v_pk_fma_f32 v[44:45], v[46:47], v[122:123], v[126:127]
	global_store_dwordx4 v110, v[0:3], s[12:13]
	global_store_dwordx4 v110, v[42:45], s[12:13] offset:16
	s_cbranch_scc0 .LBB0_578
